# M3 epilogue rewritten: head-norm weights staged once per unit in LDS (ds_read_b128 two steps ahead), output-gate loads ring-buffered three steps ahead, counted waits; replaces 16 x (store, 2 global lo
# speedup vs baseline: 1.0067x; 1.0067x over previous
.LBB0_1033:
	s_or_b64 exec, exec, s[20:21]
	s_waitcnt lgkmcnt(0)
	s_barrier
	s_and_saveexec_b64 s[20:21], s[16:17]
	s_cbranch_execz .LBB0_977
	ds_read_b128 v[10:13], v203
	ds_read_b128 v[14:17], v203 offset:32
	v_mov_b32_e32 v205, v51
	v_mov_b32_e32 v211, v51
	v_mov_b32_e32 v213, v27
	s_waitcnt lgkmcnt(1)
	v_mov_b32_e32 v30, v11
	v_mov_b32_e32 v31, v12
	v_mov_b32_e32 v11, v13
	v_pk_add_f32 v[76:77], v[72:73], v[30:31]
	v_pk_add_f32 v[74:75], v[74:75], v[10:11]
	v_pk_mul_f32 v[10:11], v[76:77], v[76:77]
	s_lshl_b32 s60, s62, 8
	v_pk_fma_f32 v[10:11], v[74:75], v[74:75], v[10:11]
	s_mov_b32 s61, s43
	v_pk_add_f32 v[30:31], v[10:11], v[10:11] op_sel:[0,1] op_sel_hi:[1,0]
	s_waitcnt lgkmcnt(0)
	v_mov_b32_e32 v10, v15
	v_mov_b32_e32 v11, v16
	v_pk_add_f32 v[72:73], v[70:71], v[10:11]
	v_mov_b32_e32 v15, v17
	ds_read_b128 v[10:13], v203 offset:64
	v_pk_add_f32 v[70:71], v[156:157], v[14:15]
	v_pk_mul_f32 v[14:15], v[72:73], v[72:73]
	v_mov_b32_e32 v31, v50
	v_pk_fma_f32 v[14:15], v[70:71], v[70:71], v[14:15]
	s_lshl_b32 s42, s62, 7
	v_pk_add_f32 v[32:33], v[14:15], v[14:15] op_sel:[0,1] op_sel_hi:[1,0]
	ds_read_b128 v[14:17], v203 offset:96
	s_waitcnt lgkmcnt(1)
	v_pk_add_f32 v[66:67], v[66:67], v[10:11]
	v_pk_add_f32 v[64:65], v[68:69], v[12:13]
	v_mul_f32_e32 v10, v67, v67
	v_pk_fma_f32 v[156:157], v[66:67], v[66:67], v[10:11] op_sel_hi:[1,1,0]
	v_mul_f32_e32 v10, v65, v65
	v_pk_fma_f32 v[68:69], v[64:65], v[64:65], v[10:11] op_sel_hi:[1,1,0]
	s_waitcnt lgkmcnt(0)
	v_add_f32_e32 v134, v58, v14
	v_add_f32_e32 v147, v59, v15
	v_add_f32_e32 v149, v60, v16
	v_add_f32_e32 v151, v61, v17
	ds_read_b128 v[10:13], v203 offset:128
	ds_read_b128 v[14:17], v203 offset:160
	v_mov_b32_e32 v157, v50
	v_mul_f32_e32 v204, v134, v134
	v_mul_f32_e32 v206, v147, v147
	v_mul_f32_e32 v208, v149, v149
	s_waitcnt lgkmcnt(0)
	v_mov_b32_e32 v33, v14
	v_mov_b32_e32 v69, v14
	v_mul_f32_e32 v210, v151, v151
	v_pk_add_f32 v[58:59], v[54:55], v[10:11]
	v_pk_add_f32 v[46:47], v[30:31], v[32:33]
	v_pk_add_f32 v[10:11], v[156:157], v[68:69]
	v_mov_b32_e32 v207, v15
	v_mov_b32_e32 v209, v15
	v_pk_add_f32 v[56:57], v[56:57], v[12:13]
	v_add_f32_e32 v61, v52, v16
	v_add_f32_e32 v60, v53, v17
	v_pk_add_f32 v[52:53], v[204:205], v[206:207]
	v_pk_add_f32 v[12:13], v[210:211], v[208:209]
	v_pk_add_f32 v[14:15], v[46:47], v[10:11]
	v_pk_mul_f32 v[10:11], v[46:47], v[10:11]
	v_mul_f32_e32 v54, v61, v61
	v_mov_b32_e32 v15, v11
	v_pk_add_f32 v[10:11], v[52:53], v[12:13]
	v_pk_mul_f32 v[12:13], v[52:53], v[12:13]
	v_mul_f32_e32 v55, v60, v60
	v_mov_b32_e32 v11, v13
	v_pk_add_f32 v[14:15], v[14:15], v[10:11]
	v_mul_f32_e32 v10, v59, v59
	v_pk_fma_f32 v[16:17], v[58:59], v[58:59], v[10:11] op_sel_hi:[1,1,0]
	v_mul_f32_e32 v10, v57, v57
	v_pk_fma_f32 v[30:31], v[56:57], v[56:57], v[10:11] op_sel_hi:[1,1,0]
	v_mov_b32_e32 v17, v55
	v_mov_b32_e32 v31, v54
	ds_read_b128 v[10:13], v203 offset:192
	v_pk_add_f32 v[16:17], v[16:17], v[30:31]
	v_mov_b32_e32 v207, v27
	v_pk_add_f32 v[14:15], v[14:15], v[16:17]
	v_mov_b32_e32 v155, v135
	v_pk_add_f32 v[30:31], v[14:15], v[14:15] op_sel:[0,1] op_sel_hi:[1,0]
	ds_read_b128 v[14:17], v203 offset:224
	s_waitcnt lgkmcnt(1)
	v_mov_b32_e32 v32, v11
	v_mov_b32_e32 v33, v12
	v_pk_add_f32 v[54:55], v[78:79], v[32:33]
	v_mov_b32_e32 v11, v13
	v_pk_add_f32 v[50:51], v[80:81], v[10:11]
	v_pk_mul_f32 v[10:11], v[54:55], v[54:55]
	s_waitcnt lgkmcnt(0)
	v_pk_add_f32 v[32:33], v[42:43], v[14:15]
	v_pk_fma_f32 v[10:11], v[50:51], v[50:51], v[10:11]
	v_pk_add_f32 v[42:43], v[44:45], v[16:17]
	v_pk_add_f32 v[68:69], v[10:11], v[10:11] op_sel:[0,1] op_sel_hi:[1,0]
	v_mul_f32_e32 v10, v33, v33
	v_pk_fma_f32 v[156:157], v[32:33], v[32:33], v[10:11] op_sel_hi:[1,1,0]
	ds_read_b128 v[10:13], v203 offset:256
	ds_read_b128 v[78:81], v203 offset:288
	v_mul_f32_e32 v14, v43, v43
	v_pk_fma_f32 v[204:205], v[42:43], v[42:43], v[14:15] op_sel_hi:[1,1,0]
	v_mov_b32_e32 v31, v26
	s_waitcnt lgkmcnt(1)
	v_add_f32_e32 v46, v38, v10
	v_add_f32_e32 v45, v39, v11
	v_add_f32_e32 v44, v40, v12
	v_add_f32_e32 v40, v41, v13
	ds_read_b128 v[10:13], v203 offset:320
	s_waitcnt lgkmcnt(1)
	v_pk_add_f32 v[16:17], v[34:35], v[78:79]
	v_pk_add_f32 v[14:15], v[36:37], v[80:81]
	ds_read_b128 v[78:81], v203 offset:352
	v_mov_b32_e32 v157, v26
	s_waitcnt lgkmcnt(1)
	v_mov_b32_e32 v69, v10
	v_mov_b32_e32 v205, v10
	v_mul_f32_e32 v206, v46, v46
	v_mul_f32_e32 v208, v45, v45
	v_mul_f32_e32 v210, v44, v44
	v_mul_f32_e32 v212, v40, v40
	v_add_f32_e32 v39, v28, v12
	v_add_f32_e32 v38, v29, v13
	v_pk_add_f32 v[28:29], v[30:31], v[68:69]
	v_pk_add_f32 v[12:13], v[156:157], v[204:205]
	v_mov_b32_e32 v209, v11
	v_mov_b32_e32 v211, v11
	v_pk_add_f32 v[30:31], v[206:207], v[208:209]
	v_pk_add_f32 v[10:11], v[212:213], v[210:211]
	v_pk_add_f32 v[26:27], v[28:29], v[12:13]
	v_pk_mul_f32 v[12:13], v[28:29], v[12:13]
	v_mul_f32_e32 v34, v39, v39
	v_mov_b32_e32 v27, v13
	v_pk_add_f32 v[12:13], v[30:31], v[10:11]
	v_pk_mul_f32 v[10:11], v[30:31], v[10:11]
	v_mul_f32_e32 v35, v38, v38
	v_mov_b32_e32 v13, v11
	v_pk_add_f32 v[10:11], v[26:27], v[12:13]
	v_mul_f32_e32 v12, v17, v17
	v_mul_f32_e32 v26, v15, v15
	v_pk_fma_f32 v[12:13], v[16:17], v[16:17], v[12:13] op_sel_hi:[1,1,0]
	v_pk_fma_f32 v[26:27], v[14:15], v[14:15], v[26:27] op_sel_hi:[1,1,0]
	v_mov_b32_e32 v13, v35
	v_mov_b32_e32 v27, v34
	v_pk_add_f32 v[12:13], v[12:13], v[26:27]
	ds_read_b128 v[208:211], v203 offset:416
	v_pk_add_f32 v[26:27], v[10:11], v[12:13]
	v_add_u32_e32 v10, s63, v172
	v_ashrrev_i32_e32 v11, 31, v10
	v_lshlrev_b64 v[10:11], 10, v[10:11]
	v_lshl_add_u64 v[10:11], s[40:41], 0, v[10:11]
	v_lshl_add_u64 v[10:11], v[10:11], 0, s[60:61]
	v_lshl_add_u64 v[12:13], s[42:43], 2, v[144:145]
	v_lshl_add_u64 v[10:11], v[10:11], 0, v[154:155]
	global_load_dwordx4 v[204:207], v[12:13], off
	global_load_dwordx2 v[68:69], v[10:11], off
	v_mbcnt_lo_u32_b32 v250, -1, 0
	v_mbcnt_hi_u32_b32 v250, -1, v250
	v_and_b32_e32 v251, 31, v250
	v_lshrrev_b32_e32 v252, 5, v250
	v_sub_u32_e32 v246, v251, v252
	v_lshlrev_b32_e32 v246, 4, v246
	v_ashrrev_i32_e32 v247, 31, v246
	v_lshl_add_u64 v[246:247], v[12:13], 0, v[246:247]
	v_bfe_u32 v252, v202, 6, 2
	v_lshlrev_b32_e32 v252, 9, v252
	v_lshl_add_u32 v252, v251, 4, v252
	v_add_u32_e32 v252, 0x12800, v252
	global_load_dwordx4 v[248:251], v[246:247], off
	v_pk_add_f32 v[156:157], v[26:27], v[26:27] op_sel:[0,1] op_sel_hi:[1,0]
	s_waitcnt lgkmcnt(1)
	v_mov_b32_e32 v26, v79
	v_mov_b32_e32 v79, v81
	v_mov_b32_e32 v27, v80
	v_pk_add_f32 v[34:35], v[62:63], v[78:79]
	ds_read_b128 v[78:81], v203 offset:384
	v_pk_add_f32 v[36:37], v[48:49], v[26:27]
	s_waitcnt lgkmcnt(1)
	v_add_f32_e32 v28, v18, v208
	v_pk_mul_f32 v[26:27], v[36:37], v[36:37]
	v_add_f32_e32 v30, v19, v209
	v_pk_fma_f32 v[26:27], v[34:35], v[34:35], v[26:27]
	v_add_f32_e32 v153, v20, v210
	v_pk_add_f32 v[48:49], v[26:27], v[26:27] op_sel:[0,1] op_sel_hi:[1,0]
	s_waitcnt lgkmcnt(0)
	v_pk_add_f32 v[26:27], v[22:23], v[78:79]
	v_add_f32_e32 v155, v21, v211
	v_mul_f32_e32 v22, v27, v27
	v_pk_fma_f32 v[62:63], v[26:27], v[26:27], v[22:23] op_sel_hi:[1,1,0]
	v_pk_add_f32 v[22:23], v[24:25], v[80:81]
	ds_read_b128 v[18:21], v203 offset:448
	ds_read_b128 v[78:81], v203 offset:480
	v_mul_f32_e32 v24, v23, v23
	v_pk_fma_f32 v[24:25], v[22:23], v[22:23], v[24:25] op_sel_hi:[1,1,0]
	v_mov_b32_e32 v157, v2
	v_mov_b32_e32 v63, v2
	s_waitcnt lgkmcnt(0)
	v_mov_b32_e32 v49, v78
	v_mov_b32_e32 v25, v78
	v_mul_f32_e32 v208, v28, v28
	v_mul_f32_e32 v210, v30, v30
	v_mul_f32_e32 v212, v153, v153
	v_mul_f32_e32 v214, v155, v155
	v_pk_add_f32 v[8:9], v[8:9], v[20:21]
	v_add_f32_e32 v21, v4, v80
	v_add_f32_e32 v20, v5, v81
	v_pk_add_f32 v[4:5], v[156:157], v[48:49]
	v_pk_add_f32 v[24:25], v[62:63], v[24:25]
	v_mov_b32_e32 v209, v3
	v_mov_b32_e32 v211, v79
	v_mov_b32_e32 v215, v3
	v_mov_b32_e32 v213, v79
	v_pk_add_f32 v[18:19], v[6:7], v[18:19]
	v_pk_add_f32 v[6:7], v[208:209], v[210:211]
	v_pk_add_f32 v[2:3], v[214:215], v[212:213]
	v_pk_add_f32 v[48:49], v[4:5], v[24:25]
	v_pk_mul_f32 v[24:25], v[4:5], v[24:25]
	v_mul_f32_e32 v4, v19, v19
	v_mov_b32_e32 v49, v25
	v_pk_add_f32 v[24:25], v[6:7], v[2:3]
	v_pk_mul_f32 v[2:3], v[6:7], v[2:3]
	v_mul_f32_e32 v41, v21, v21
	v_mov_b32_e32 v25, v3
	v_pk_add_f32 v[2:3], v[48:49], v[24:25]
	v_pk_fma_f32 v[24:25], v[18:19], v[18:19], v[4:5] op_sel_hi:[1,1,0]
	v_mul_f32_e32 v4, v9, v9
	v_mul_f32_e32 v52, v20, v20
	v_pk_fma_f32 v[48:49], v[8:9], v[8:9], v[4:5] op_sel_hi:[1,1,0]
	v_mov_b32_e32 v25, v52
	v_mov_b32_e32 v49, v41
	v_pk_add_f32 v[24:25], v[24:25], v[48:49]
	s_waitcnt vmcnt(0)
	ds_write_b128 v252, v[248:251]
	v_lshlrev_b32_e32 v4, 16, v68
	v_pk_add_f32 v[2:3], v[2:3], v[24:25]
	v_and_b32_e32 v6, 0xffff0000, v68
	v_add_f32_e32 v2, v2, v3
	ds_bpermute_b32 v3, v176, v2
	s_waitcnt lgkmcnt(0)
	v_add_f32_e32 v2, v2, v3
	v_fmamk_f32 v2, v2, 0x3c000000, v200
	v_mul_f32_e32 v3, 0x4b800000, v2
	v_cmp_gt_f32_e32 vcc, s47, v2
	s_nop 1
	v_cndmask_b32_e32 v2, v2, v3, vcc
	v_rsq_f32_e32 v2, v2
	s_nop 0
	v_mul_f32_e32 v3, 0x45800000, v2
	v_cndmask_b32_e32 v2, v2, v3, vcc
	s_waitcnt lgkmcnt(0)
	v_mbcnt_lo_u32_b32 v252, -1, 0
	v_mbcnt_hi_u32_b32 v252, -1, v252
	v_lshrrev_b32_e32 v252, 5, v252
	v_lshlrev_b32_e32 v252, 4, v252
	v_bfe_u32 v246, v202, 6, 2
	v_lshl_add_u32 v252, v246, 9, v252
	v_add_u32_e32 v252, 0x12800, v252
	global_load_dwordx2 v[242:243], v[10:11], off offset:16
	global_load_dwordx2 v[244:245], v[10:11], off offset:32
	global_load_dwordx2 v[246:247], v[10:11], off offset:48
	ds_read_b128 v[248:251], v252 offset:32
	v_mul_f32_e32 v3, v74, v2
	v_mul_f32_e32 v3, v204, v3
	v_lshlrev_b32_e32 v25, 16, v68
	v_mul_f32_e32 v3, v3, v25
	v_mul_f32_e32 v4, v76, v2
	v_mul_f32_e32 v4, v205, v4
	v_and_b32_e32 v25, 0xffff0000, v68
	v_mul_f32_e32 v4, v4, v25
	v_mul_f32_e32 v6, v77, v2
	v_mul_f32_e32 v6, v206, v6
	v_lshlrev_b32_e32 v25, 16, v69
	v_mul_f32_e32 v6, v6, v25
	v_mul_f32_e32 v41, v75, v2
	v_mul_f32_e32 v41, v207, v41
	v_and_b32_e32 v25, 0xffff0000, v69
	v_mul_f32_e32 v41, v41, v25
	v_cvt_pk_bf16_f32 v68, v3, v4
	v_cvt_pk_bf16_f32 v69, v6, v41
	global_store_dwordx2 v[10:11], v[68:69], off
	ds_read_b128 v[204:207], v252 offset:64
	s_waitcnt lgkmcnt(1)
	s_waitcnt vmcnt(3)
	v_mul_f32_e32 v3, v70, v2
	v_mul_f32_e32 v3, v248, v3
	v_lshlrev_b32_e32 v25, 16, v242
	v_mul_f32_e32 v3, v3, v25
	v_mul_f32_e32 v4, v72, v2
	v_mul_f32_e32 v4, v249, v4
	v_and_b32_e32 v25, 0xffff0000, v242
	v_mul_f32_e32 v4, v4, v25
	v_mul_f32_e32 v6, v73, v2
	v_mul_f32_e32 v6, v250, v6
	v_lshlrev_b32_e32 v25, 16, v243
	v_mul_f32_e32 v6, v6, v25
	v_mul_f32_e32 v41, v71, v2
	v_mul_f32_e32 v41, v251, v41
	v_and_b32_e32 v25, 0xffff0000, v243
	v_mul_f32_e32 v41, v41, v25
	v_cvt_pk_bf16_f32 v242, v3, v4
	v_cvt_pk_bf16_f32 v243, v6, v41
	global_store_dwordx2 v[10:11], v[242:243], off offset:16
	ds_read_b128 v[248:251], v252 offset:96
	global_load_dwordx2 v[242:243], v[10:11], off offset:64
	s_waitcnt lgkmcnt(1)
	s_waitcnt vmcnt(4)
	v_mul_f32_e32 v3, v66, v2
	v_mul_f32_e32 v3, v204, v3
	v_lshlrev_b32_e32 v25, 16, v244
	v_mul_f32_e32 v3, v3, v25
	v_mul_f32_e32 v4, v67, v2
	v_mul_f32_e32 v4, v205, v4
	v_and_b32_e32 v25, 0xffff0000, v244
	v_mul_f32_e32 v4, v4, v25
	v_mul_f32_e32 v6, v64, v2
	v_mul_f32_e32 v6, v206, v6
	v_lshlrev_b32_e32 v25, 16, v245
	v_mul_f32_e32 v6, v6, v25
	v_mul_f32_e32 v41, v65, v2
	v_mul_f32_e32 v41, v207, v41
	v_and_b32_e32 v25, 0xffff0000, v245
	v_mul_f32_e32 v41, v41, v25
	v_cvt_pk_bf16_f32 v244, v3, v4
	v_cvt_pk_bf16_f32 v245, v6, v41
	global_store_dwordx2 v[10:11], v[244:245], off offset:32
	ds_read_b128 v[204:207], v252 offset:128
	global_load_dwordx2 v[244:245], v[10:11], off offset:80
	s_waitcnt lgkmcnt(1)
	s_waitcnt vmcnt(5)
	v_mul_f32_e32 v3, v134, v2
	v_mul_f32_e32 v3, v248, v3
	v_lshlrev_b32_e32 v25, 16, v246
	v_mul_f32_e32 v3, v3, v25
	v_mul_f32_e32 v4, v147, v2
	v_mul_f32_e32 v4, v249, v4
	v_and_b32_e32 v25, 0xffff0000, v246
	v_mul_f32_e32 v4, v4, v25
	v_mul_f32_e32 v6, v149, v2
	v_mul_f32_e32 v6, v250, v6
	v_lshlrev_b32_e32 v25, 16, v247
	v_mul_f32_e32 v6, v6, v25
	v_mul_f32_e32 v41, v151, v2
	v_mul_f32_e32 v41, v251, v41
	v_and_b32_e32 v25, 0xffff0000, v247
	v_mul_f32_e32 v41, v41, v25
	v_cvt_pk_bf16_f32 v246, v3, v4
	v_cvt_pk_bf16_f32 v247, v6, v41
	global_store_dwordx2 v[10:11], v[246:247], off offset:48
	ds_read_b128 v[248:251], v252 offset:160
	global_load_dwordx2 v[246:247], v[10:11], off offset:96
	s_waitcnt lgkmcnt(1)
	s_waitcnt vmcnt(4)
	v_mul_f32_e32 v3, v58, v2
	v_mul_f32_e32 v3, v204, v3
	v_lshlrev_b32_e32 v25, 16, v242
	v_mul_f32_e32 v3, v3, v25
	v_mul_f32_e32 v4, v59, v2
	v_mul_f32_e32 v4, v205, v4
	v_and_b32_e32 v25, 0xffff0000, v242
	v_mul_f32_e32 v4, v4, v25
	v_mul_f32_e32 v6, v56, v2
	v_mul_f32_e32 v6, v206, v6
	v_lshlrev_b32_e32 v25, 16, v243
	v_mul_f32_e32 v6, v6, v25
	v_mul_f32_e32 v41, v57, v2
	v_mul_f32_e32 v41, v207, v41
	v_and_b32_e32 v25, 0xffff0000, v243
	v_mul_f32_e32 v41, v41, v25
	v_cvt_pk_bf16_f32 v242, v3, v4
	v_cvt_pk_bf16_f32 v243, v6, v41
	global_store_dwordx2 v[10:11], v[242:243], off offset:64
	ds_read_b128 v[204:207], v252 offset:192
	global_load_dwordx2 v[242:243], v[10:11], off offset:112
	s_waitcnt lgkmcnt(1)
	s_waitcnt vmcnt(4)
	v_mul_f32_e32 v3, v47, v2
	v_mul_f32_e32 v3, v248, v3
	v_lshlrev_b32_e32 v25, 16, v244
	v_mul_f32_e32 v3, v3, v25
	v_mul_f32_e32 v4, v53, v2
	v_mul_f32_e32 v4, v249, v4
	v_and_b32_e32 v25, 0xffff0000, v244
	v_mul_f32_e32 v4, v4, v25
	v_mul_f32_e32 v6, v61, v2
	v_mul_f32_e32 v6, v250, v6
	v_lshlrev_b32_e32 v25, 16, v245
	v_mul_f32_e32 v6, v6, v25
	v_mul_f32_e32 v41, v60, v2
	v_mul_f32_e32 v41, v251, v41
	v_and_b32_e32 v25, 0xffff0000, v245
	v_mul_f32_e32 v41, v41, v25
	v_cvt_pk_bf16_f32 v244, v3, v4
	v_cvt_pk_bf16_f32 v245, v6, v41
	global_store_dwordx2 v[10:11], v[244:245], off offset:80
	ds_read_b128 v[248:251], v252 offset:224
	global_load_dwordx2 v[244:245], v[10:11], off offset:128
	s_waitcnt lgkmcnt(1)
	s_waitcnt vmcnt(4)
	v_mul_f32_e32 v3, v50, v2
	v_mul_f32_e32 v3, v204, v3
	v_lshlrev_b32_e32 v25, 16, v246
	v_mul_f32_e32 v3, v3, v25
	v_mul_f32_e32 v4, v54, v2
	v_mul_f32_e32 v4, v205, v4
	v_and_b32_e32 v25, 0xffff0000, v246
	v_mul_f32_e32 v4, v4, v25
	v_mul_f32_e32 v6, v55, v2
	v_mul_f32_e32 v6, v206, v6
	v_lshlrev_b32_e32 v25, 16, v247
	v_mul_f32_e32 v6, v6, v25
	v_mul_f32_e32 v41, v51, v2
	v_mul_f32_e32 v41, v207, v41
	v_and_b32_e32 v25, 0xffff0000, v247
	v_mul_f32_e32 v41, v41, v25
	v_cvt_pk_bf16_f32 v246, v3, v4
	v_cvt_pk_bf16_f32 v247, v6, v41
	global_store_dwordx2 v[10:11], v[246:247], off offset:96
	ds_read_b128 v[204:207], v252 offset:256
	global_load_dwordx2 v[246:247], v[10:11], off offset:144
	s_waitcnt lgkmcnt(1)
	s_waitcnt vmcnt(4)
	v_mul_f32_e32 v3, v32, v2
	v_mul_f32_e32 v3, v248, v3
	v_lshlrev_b32_e32 v25, 16, v242
	v_mul_f32_e32 v3, v3, v25
	v_mul_f32_e32 v4, v33, v2
	v_mul_f32_e32 v4, v249, v4
	v_and_b32_e32 v25, 0xffff0000, v242
	v_mul_f32_e32 v4, v4, v25
	v_mul_f32_e32 v6, v42, v2
	v_mul_f32_e32 v6, v250, v6
	v_lshlrev_b32_e32 v25, 16, v243
	v_mul_f32_e32 v6, v6, v25
	v_mul_f32_e32 v41, v43, v2
	v_mul_f32_e32 v41, v251, v41
	v_and_b32_e32 v25, 0xffff0000, v243
	v_mul_f32_e32 v41, v41, v25
	v_cvt_pk_bf16_f32 v242, v3, v4
	v_cvt_pk_bf16_f32 v243, v6, v41
	global_store_dwordx2 v[10:11], v[242:243], off offset:112
	ds_read_b128 v[248:251], v252 offset:288
	global_load_dwordx2 v[242:243], v[10:11], off offset:160
	s_waitcnt lgkmcnt(1)
	s_waitcnt vmcnt(4)
	v_mul_f32_e32 v3, v46, v2
	v_mul_f32_e32 v3, v204, v3
	v_lshlrev_b32_e32 v25, 16, v244
	v_mul_f32_e32 v3, v3, v25
	v_mul_f32_e32 v4, v45, v2
	v_mul_f32_e32 v4, v205, v4
	v_and_b32_e32 v25, 0xffff0000, v244
	v_mul_f32_e32 v4, v4, v25
	v_mul_f32_e32 v6, v44, v2
	v_mul_f32_e32 v6, v206, v6
	v_lshlrev_b32_e32 v25, 16, v245
	v_mul_f32_e32 v6, v6, v25
	v_mul_f32_e32 v41, v40, v2
	v_mul_f32_e32 v41, v207, v41
	v_and_b32_e32 v25, 0xffff0000, v245
	v_mul_f32_e32 v41, v41, v25
	v_cvt_pk_bf16_f32 v244, v3, v4
	v_cvt_pk_bf16_f32 v245, v6, v41
	global_store_dwordx2 v[10:11], v[244:245], off offset:128
	ds_read_b128 v[204:207], v252 offset:320
	global_load_dwordx2 v[244:245], v[10:11], off offset:176
	s_waitcnt lgkmcnt(1)
	s_waitcnt vmcnt(4)
	v_mul_f32_e32 v3, v16, v2
	v_mul_f32_e32 v3, v248, v3
	v_lshlrev_b32_e32 v25, 16, v246
	v_mul_f32_e32 v3, v3, v25
	v_mul_f32_e32 v4, v17, v2
	v_mul_f32_e32 v4, v249, v4
	v_and_b32_e32 v25, 0xffff0000, v246
	v_mul_f32_e32 v4, v4, v25
	v_mul_f32_e32 v6, v14, v2
	v_mul_f32_e32 v6, v250, v6
	v_lshlrev_b32_e32 v25, 16, v247
	v_mul_f32_e32 v6, v6, v25
	v_mul_f32_e32 v41, v15, v2
	v_mul_f32_e32 v41, v251, v41
	v_and_b32_e32 v25, 0xffff0000, v247
	v_mul_f32_e32 v41, v41, v25
	v_cvt_pk_bf16_f32 v246, v3, v4
	v_cvt_pk_bf16_f32 v247, v6, v41
	global_store_dwordx2 v[10:11], v[246:247], off offset:144
	ds_read_b128 v[248:251], v252 offset:352
	global_load_dwordx2 v[246:247], v[10:11], off offset:192
	s_waitcnt lgkmcnt(1)
	s_waitcnt vmcnt(4)
	v_mul_f32_e32 v3, v29, v2
	v_mul_f32_e32 v3, v204, v3
	v_lshlrev_b32_e32 v25, 16, v242
	v_mul_f32_e32 v3, v3, v25
	v_mul_f32_e32 v4, v31, v2
	v_mul_f32_e32 v4, v205, v4
	v_and_b32_e32 v25, 0xffff0000, v242
	v_mul_f32_e32 v4, v4, v25
	v_mul_f32_e32 v6, v39, v2
	v_mul_f32_e32 v6, v206, v6
	v_lshlrev_b32_e32 v25, 16, v243
	v_mul_f32_e32 v6, v6, v25
	v_mul_f32_e32 v41, v38, v2
	v_mul_f32_e32 v41, v207, v41
	v_and_b32_e32 v25, 0xffff0000, v243
	v_mul_f32_e32 v41, v41, v25
	v_cvt_pk_bf16_f32 v242, v3, v4
	v_cvt_pk_bf16_f32 v243, v6, v41
	global_store_dwordx2 v[10:11], v[242:243], off offset:160
	ds_read_b128 v[204:207], v252 offset:384
	global_load_dwordx2 v[242:243], v[10:11], off offset:208
	s_waitcnt lgkmcnt(1)
	s_waitcnt vmcnt(4)
	v_mul_f32_e32 v3, v34, v2
	v_mul_f32_e32 v3, v248, v3
	v_lshlrev_b32_e32 v25, 16, v244
	v_mul_f32_e32 v3, v3, v25
	v_mul_f32_e32 v4, v36, v2
	v_mul_f32_e32 v4, v249, v4
	v_and_b32_e32 v25, 0xffff0000, v244
	v_mul_f32_e32 v4, v4, v25
	v_mul_f32_e32 v6, v37, v2
	v_mul_f32_e32 v6, v250, v6
	v_lshlrev_b32_e32 v25, 16, v245
	v_mul_f32_e32 v6, v6, v25
	v_mul_f32_e32 v41, v35, v2
	v_mul_f32_e32 v41, v251, v41
	v_and_b32_e32 v25, 0xffff0000, v245
	v_mul_f32_e32 v41, v41, v25
	v_cvt_pk_bf16_f32 v244, v3, v4
	v_cvt_pk_bf16_f32 v245, v6, v41
	global_store_dwordx2 v[10:11], v[244:245], off offset:176
	ds_read_b128 v[248:251], v252 offset:416
	global_load_dwordx2 v[244:245], v[10:11], off offset:224
	s_waitcnt lgkmcnt(1)
	s_waitcnt vmcnt(4)
	v_mul_f32_e32 v3, v26, v2
	v_mul_f32_e32 v3, v204, v3
	v_lshlrev_b32_e32 v25, 16, v246
	v_mul_f32_e32 v3, v3, v25
	v_mul_f32_e32 v4, v27, v2
	v_mul_f32_e32 v4, v205, v4
	v_and_b32_e32 v25, 0xffff0000, v246
	v_mul_f32_e32 v4, v4, v25
	v_mul_f32_e32 v6, v22, v2
	v_mul_f32_e32 v6, v206, v6
	v_lshlrev_b32_e32 v25, 16, v247
	v_mul_f32_e32 v6, v6, v25
	v_mul_f32_e32 v41, v23, v2
	v_mul_f32_e32 v41, v207, v41
	v_and_b32_e32 v25, 0xffff0000, v247
	v_mul_f32_e32 v41, v41, v25
	v_cvt_pk_bf16_f32 v246, v3, v4
	v_cvt_pk_bf16_f32 v247, v6, v41
	global_store_dwordx2 v[10:11], v[246:247], off offset:192
	ds_read_b128 v[204:207], v252 offset:448
	global_load_dwordx2 v[246:247], v[10:11], off offset:240
	s_waitcnt lgkmcnt(1)
	s_waitcnt vmcnt(4)
	v_mul_f32_e32 v3, v28, v2
	v_mul_f32_e32 v3, v248, v3
	v_lshlrev_b32_e32 v25, 16, v242
	v_mul_f32_e32 v3, v3, v25
	v_mul_f32_e32 v4, v30, v2
	v_mul_f32_e32 v4, v249, v4
	v_and_b32_e32 v25, 0xffff0000, v242
	v_mul_f32_e32 v4, v4, v25
	v_mul_f32_e32 v6, v153, v2
	v_mul_f32_e32 v6, v250, v6
	v_lshlrev_b32_e32 v25, 16, v243
	v_mul_f32_e32 v6, v6, v25
	v_mul_f32_e32 v41, v155, v2
	v_mul_f32_e32 v41, v251, v41
	v_and_b32_e32 v25, 0xffff0000, v243
	v_mul_f32_e32 v41, v41, v25
	v_cvt_pk_bf16_f32 v242, v3, v4
	v_cvt_pk_bf16_f32 v243, v6, v41
	global_store_dwordx2 v[10:11], v[242:243], off offset:208
	ds_read_b128 v[248:251], v252 offset:480
	s_waitcnt lgkmcnt(1)
	s_waitcnt vmcnt(3)
	v_mul_f32_e32 v3, v18, v2
	v_mul_f32_e32 v3, v204, v3
	v_lshlrev_b32_e32 v25, 16, v244
	v_mul_f32_e32 v3, v3, v25
	v_mul_f32_e32 v4, v19, v2
	v_mul_f32_e32 v4, v205, v4
	v_and_b32_e32 v25, 0xffff0000, v244
	v_mul_f32_e32 v4, v4, v25
	v_mul_f32_e32 v6, v8, v2
	v_mul_f32_e32 v6, v206, v6
	v_lshlrev_b32_e32 v25, 16, v245
	v_mul_f32_e32 v6, v6, v25
	v_mul_f32_e32 v41, v9, v2
	v_mul_f32_e32 v41, v207, v41
	v_and_b32_e32 v25, 0xffff0000, v245
	v_mul_f32_e32 v41, v41, v25
	v_cvt_pk_bf16_f32 v244, v3, v4
	v_cvt_pk_bf16_f32 v245, v6, v41
	global_store_dwordx2 v[10:11], v[244:245], off offset:224
	s_waitcnt lgkmcnt(0)
	s_waitcnt vmcnt(2)
	v_mul_f32_e32 v3, v5, v2
	v_mul_f32_e32 v3, v248, v3
	v_lshlrev_b32_e32 v25, 16, v246
	v_mul_f32_e32 v3, v3, v25
	v_mul_f32_e32 v4, v7, v2
	v_mul_f32_e32 v4, v249, v4
	v_and_b32_e32 v25, 0xffff0000, v246
	v_mul_f32_e32 v4, v4, v25
	v_mul_f32_e32 v6, v21, v2
	v_mul_f32_e32 v6, v250, v6
	v_lshlrev_b32_e32 v25, 16, v247
	v_mul_f32_e32 v6, v6, v25
	v_mul_f32_e32 v41, v20, v2
	v_mul_f32_e32 v41, v251, v41
	v_and_b32_e32 v25, 0xffff0000, v247
	v_mul_f32_e32 v41, v41, v25
	v_cvt_pk_bf16_f32 v246, v3, v4
	v_cvt_pk_bf16_f32 v247, v6, v41
	global_store_dwordx2 v[10:11], v[246:247], off offset:240
	s_branch .LBB0_977

.LBB0_1207:
	s_or_b64 exec, exec, s[20:21]
	s_waitcnt lgkmcnt(0)
	s_barrier
	s_and_saveexec_b64 s[20:21], s[16:17]
	s_cbranch_execz .LBB0_1133
	ds_read_b128 v[10:13], v203
	ds_read_b128 v[14:17], v203 offset:32
	v_mov_b32_e32 v205, v51
	v_mov_b32_e32 v211, v51
	v_mov_b32_e32 v213, v27
	s_waitcnt lgkmcnt(1)
	v_mov_b32_e32 v30, v11
	v_mov_b32_e32 v31, v12
	v_mov_b32_e32 v11, v13
	v_pk_add_f32 v[76:77], v[72:73], v[30:31]
	v_pk_add_f32 v[74:75], v[74:75], v[10:11]
	v_pk_mul_f32 v[10:11], v[76:77], v[76:77]
	s_lshl_b32 s22, s68, 8
	v_pk_fma_f32 v[10:11], v[74:75], v[74:75], v[10:11]
	s_mov_b32 s23, s47
	v_pk_add_f32 v[30:31], v[10:11], v[10:11] op_sel:[0,1] op_sel_hi:[1,0]
	s_waitcnt lgkmcnt(0)
	v_mov_b32_e32 v10, v15
	v_mov_b32_e32 v11, v16
	v_pk_add_f32 v[72:73], v[70:71], v[10:11]
	v_mov_b32_e32 v15, v17
	ds_read_b128 v[10:13], v203 offset:64
	v_pk_add_f32 v[70:71], v[156:157], v[14:15]
	v_pk_mul_f32 v[14:15], v[72:73], v[72:73]
	v_mov_b32_e32 v31, v50
	v_pk_fma_f32 v[14:15], v[70:71], v[70:71], v[14:15]
	s_lshl_b32 s46, s68, 7
	v_pk_add_f32 v[32:33], v[14:15], v[14:15] op_sel:[0,1] op_sel_hi:[1,0]
	ds_read_b128 v[14:17], v203 offset:96
	s_waitcnt lgkmcnt(1)
	v_pk_add_f32 v[66:67], v[66:67], v[10:11]
	v_pk_add_f32 v[64:65], v[68:69], v[12:13]
	v_mul_f32_e32 v10, v67, v67
	v_pk_fma_f32 v[156:157], v[66:67], v[66:67], v[10:11] op_sel_hi:[1,1,0]
	v_mul_f32_e32 v10, v65, v65
	v_pk_fma_f32 v[68:69], v[64:65], v[64:65], v[10:11] op_sel_hi:[1,1,0]
	s_waitcnt lgkmcnt(0)
	v_add_f32_e32 v134, v58, v14
	v_add_f32_e32 v147, v59, v15
	v_add_f32_e32 v149, v60, v16
	v_add_f32_e32 v151, v61, v17
	ds_read_b128 v[10:13], v203 offset:128
	ds_read_b128 v[14:17], v203 offset:160
	v_mov_b32_e32 v157, v50
	v_mul_f32_e32 v204, v134, v134
	v_mul_f32_e32 v206, v147, v147
	v_mul_f32_e32 v208, v149, v149
	s_waitcnt lgkmcnt(0)
	v_mov_b32_e32 v33, v14
	v_mov_b32_e32 v69, v14
	v_mul_f32_e32 v210, v151, v151
	v_pk_add_f32 v[58:59], v[54:55], v[10:11]
	v_pk_add_f32 v[46:47], v[30:31], v[32:33]
	v_pk_add_f32 v[10:11], v[156:157], v[68:69]
	v_mov_b32_e32 v207, v15
	v_mov_b32_e32 v209, v15
	v_pk_add_f32 v[56:57], v[56:57], v[12:13]
	v_add_f32_e32 v61, v52, v16
	v_add_f32_e32 v60, v53, v17
	v_pk_add_f32 v[52:53], v[204:205], v[206:207]
	v_pk_add_f32 v[12:13], v[210:211], v[208:209]
	v_pk_add_f32 v[14:15], v[46:47], v[10:11]
	v_pk_mul_f32 v[10:11], v[46:47], v[10:11]
	v_mul_f32_e32 v54, v61, v61
	v_mov_b32_e32 v15, v11
	v_pk_add_f32 v[10:11], v[52:53], v[12:13]
	v_pk_mul_f32 v[12:13], v[52:53], v[12:13]
	v_mul_f32_e32 v55, v60, v60
	v_mov_b32_e32 v11, v13
	v_pk_add_f32 v[14:15], v[14:15], v[10:11]
	v_mul_f32_e32 v10, v59, v59
	v_pk_fma_f32 v[16:17], v[58:59], v[58:59], v[10:11] op_sel_hi:[1,1,0]
	v_mul_f32_e32 v10, v57, v57
	v_pk_fma_f32 v[30:31], v[56:57], v[56:57], v[10:11] op_sel_hi:[1,1,0]
	v_mov_b32_e32 v17, v55
	v_mov_b32_e32 v31, v54
	ds_read_b128 v[10:13], v203 offset:192
	v_pk_add_f32 v[16:17], v[16:17], v[30:31]
	v_mov_b32_e32 v207, v27
	v_pk_add_f32 v[14:15], v[14:15], v[16:17]
	v_mov_b32_e32 v155, v135
	v_pk_add_f32 v[30:31], v[14:15], v[14:15] op_sel:[0,1] op_sel_hi:[1,0]
	ds_read_b128 v[14:17], v203 offset:224
	s_waitcnt lgkmcnt(1)
	v_mov_b32_e32 v32, v11
	v_mov_b32_e32 v33, v12
	v_pk_add_f32 v[54:55], v[78:79], v[32:33]
	v_mov_b32_e32 v11, v13
	v_pk_add_f32 v[50:51], v[80:81], v[10:11]
	v_pk_mul_f32 v[10:11], v[54:55], v[54:55]
	s_waitcnt lgkmcnt(0)
	v_pk_add_f32 v[32:33], v[42:43], v[14:15]
	v_pk_fma_f32 v[10:11], v[50:51], v[50:51], v[10:11]
	v_pk_add_f32 v[42:43], v[44:45], v[16:17]
	v_pk_add_f32 v[68:69], v[10:11], v[10:11] op_sel:[0,1] op_sel_hi:[1,0]
	v_mul_f32_e32 v10, v33, v33
	v_pk_fma_f32 v[156:157], v[32:33], v[32:33], v[10:11] op_sel_hi:[1,1,0]
	ds_read_b128 v[10:13], v203 offset:256
	ds_read_b128 v[78:81], v203 offset:288
	v_mul_f32_e32 v14, v43, v43
	v_pk_fma_f32 v[204:205], v[42:43], v[42:43], v[14:15] op_sel_hi:[1,1,0]
	v_mov_b32_e32 v31, v26
	s_waitcnt lgkmcnt(1)
	v_add_f32_e32 v46, v38, v10
	v_add_f32_e32 v45, v39, v11
	v_add_f32_e32 v44, v40, v12
	v_add_f32_e32 v40, v41, v13
	ds_read_b128 v[10:13], v203 offset:320
	s_waitcnt lgkmcnt(1)
	v_pk_add_f32 v[16:17], v[34:35], v[78:79]
	v_pk_add_f32 v[14:15], v[36:37], v[80:81]
	ds_read_b128 v[78:81], v203 offset:352
	v_mov_b32_e32 v157, v26
	s_waitcnt lgkmcnt(1)
	v_mov_b32_e32 v69, v10
	v_mov_b32_e32 v205, v10
	v_mul_f32_e32 v206, v46, v46
	v_mul_f32_e32 v208, v45, v45
	v_mul_f32_e32 v210, v44, v44
	v_mul_f32_e32 v212, v40, v40
	v_add_f32_e32 v39, v28, v12
	v_add_f32_e32 v38, v29, v13
	v_pk_add_f32 v[28:29], v[30:31], v[68:69]
	v_pk_add_f32 v[12:13], v[156:157], v[204:205]
	v_mov_b32_e32 v209, v11
	v_mov_b32_e32 v211, v11
	v_pk_add_f32 v[30:31], v[206:207], v[208:209]
	v_pk_add_f32 v[10:11], v[212:213], v[210:211]
	v_pk_add_f32 v[26:27], v[28:29], v[12:13]
	v_pk_mul_f32 v[12:13], v[28:29], v[12:13]
	v_mul_f32_e32 v34, v39, v39
	v_mov_b32_e32 v27, v13
	v_pk_add_f32 v[12:13], v[30:31], v[10:11]
	v_pk_mul_f32 v[10:11], v[30:31], v[10:11]
	v_mul_f32_e32 v35, v38, v38
	v_mov_b32_e32 v13, v11
	v_pk_add_f32 v[10:11], v[26:27], v[12:13]
	v_mul_f32_e32 v12, v17, v17
	v_mul_f32_e32 v26, v15, v15
	v_pk_fma_f32 v[12:13], v[16:17], v[16:17], v[12:13] op_sel_hi:[1,1,0]
	v_pk_fma_f32 v[26:27], v[14:15], v[14:15], v[26:27] op_sel_hi:[1,1,0]
	v_mov_b32_e32 v13, v35
	v_mov_b32_e32 v27, v34
	v_pk_add_f32 v[12:13], v[12:13], v[26:27]
	ds_read_b128 v[208:211], v203 offset:416
	v_pk_add_f32 v[26:27], v[10:11], v[12:13]
	v_add_u32_e32 v10, s39, v171
	v_ashrrev_i32_e32 v11, 31, v10
	v_lshlrev_b64 v[10:11], 10, v[10:11]
	v_lshl_add_u64 v[10:11], s[44:45], 0, v[10:11]
	v_lshl_add_u64 v[10:11], v[10:11], 0, s[22:23]
	v_lshl_add_u64 v[12:13], s[46:47], 2, v[144:145]
	v_lshl_add_u64 v[10:11], v[10:11], 0, v[154:155]
	global_load_dwordx4 v[204:207], v[12:13], off
	global_load_dwordx2 v[68:69], v[10:11], off
	v_mbcnt_lo_u32_b32 v250, -1, 0
	v_mbcnt_hi_u32_b32 v250, -1, v250
	v_and_b32_e32 v251, 31, v250
	v_lshrrev_b32_e32 v252, 5, v250
	v_sub_u32_e32 v246, v251, v252
	v_lshlrev_b32_e32 v246, 4, v246
	v_ashrrev_i32_e32 v247, 31, v246
	v_lshl_add_u64 v[246:247], v[12:13], 0, v[246:247]
	v_bfe_u32 v252, v202, 6, 2
	v_lshlrev_b32_e32 v252, 9, v252
	v_lshl_add_u32 v252, v251, 4, v252
	v_add_u32_e32 v252, 0x12800, v252
	global_load_dwordx4 v[248:251], v[246:247], off
	v_pk_add_f32 v[156:157], v[26:27], v[26:27] op_sel:[0,1] op_sel_hi:[1,0]
	s_waitcnt lgkmcnt(1)
	v_mov_b32_e32 v26, v79
	v_mov_b32_e32 v79, v81
	v_mov_b32_e32 v27, v80
	v_pk_add_f32 v[34:35], v[62:63], v[78:79]
	ds_read_b128 v[78:81], v203 offset:384
	v_pk_add_f32 v[36:37], v[48:49], v[26:27]
	s_waitcnt lgkmcnt(1)
	v_add_f32_e32 v28, v18, v208
	v_pk_mul_f32 v[26:27], v[36:37], v[36:37]
	v_add_f32_e32 v30, v19, v209
	v_pk_fma_f32 v[26:27], v[34:35], v[34:35], v[26:27]
	v_add_f32_e32 v153, v20, v210
	v_pk_add_f32 v[48:49], v[26:27], v[26:27] op_sel:[0,1] op_sel_hi:[1,0]
	s_waitcnt lgkmcnt(0)
	v_pk_add_f32 v[26:27], v[22:23], v[78:79]
	v_add_f32_e32 v155, v21, v211
	v_mul_f32_e32 v22, v27, v27
	v_pk_fma_f32 v[62:63], v[26:27], v[26:27], v[22:23] op_sel_hi:[1,1,0]
	v_pk_add_f32 v[22:23], v[24:25], v[80:81]
	ds_read_b128 v[18:21], v203 offset:448
	ds_read_b128 v[78:81], v203 offset:480
	v_mul_f32_e32 v24, v23, v23
	v_pk_fma_f32 v[24:25], v[22:23], v[22:23], v[24:25] op_sel_hi:[1,1,0]
	v_mov_b32_e32 v157, v2
	v_mov_b32_e32 v63, v2
	s_waitcnt lgkmcnt(0)
	v_mov_b32_e32 v49, v78
	v_mov_b32_e32 v25, v78
	v_mul_f32_e32 v208, v28, v28
	v_mul_f32_e32 v210, v30, v30
	v_mul_f32_e32 v212, v153, v153
	v_mul_f32_e32 v214, v155, v155
	v_pk_add_f32 v[8:9], v[8:9], v[20:21]
	v_add_f32_e32 v21, v4, v80
	v_add_f32_e32 v20, v5, v81
	v_pk_add_f32 v[4:5], v[156:157], v[48:49]
	v_pk_add_f32 v[24:25], v[62:63], v[24:25]
	v_mov_b32_e32 v209, v3
	v_mov_b32_e32 v211, v79
	v_mov_b32_e32 v215, v3
	v_mov_b32_e32 v213, v79
	v_pk_add_f32 v[18:19], v[6:7], v[18:19]
	v_pk_add_f32 v[6:7], v[208:209], v[210:211]
	v_pk_add_f32 v[2:3], v[214:215], v[212:213]
	v_pk_add_f32 v[48:49], v[4:5], v[24:25]
	v_pk_mul_f32 v[24:25], v[4:5], v[24:25]
	v_mul_f32_e32 v4, v19, v19
	v_mov_b32_e32 v49, v25
	v_pk_add_f32 v[24:25], v[6:7], v[2:3]
	v_pk_mul_f32 v[2:3], v[6:7], v[2:3]
	v_mul_f32_e32 v41, v21, v21
	v_mov_b32_e32 v25, v3
	v_pk_add_f32 v[2:3], v[48:49], v[24:25]
	v_pk_fma_f32 v[24:25], v[18:19], v[18:19], v[4:5] op_sel_hi:[1,1,0]
	v_mul_f32_e32 v4, v9, v9
	v_mul_f32_e32 v52, v20, v20
	v_pk_fma_f32 v[48:49], v[8:9], v[8:9], v[4:5] op_sel_hi:[1,1,0]
	v_mov_b32_e32 v25, v52
	v_mov_b32_e32 v49, v41
	v_pk_add_f32 v[24:25], v[24:25], v[48:49]
	s_waitcnt vmcnt(0)
	ds_write_b128 v252, v[248:251]
	v_lshlrev_b32_e32 v4, 16, v68
	v_pk_add_f32 v[2:3], v[2:3], v[24:25]
	v_and_b32_e32 v6, 0xffff0000, v68
	v_add_f32_e32 v2, v2, v3
	ds_bpermute_b32 v3, v175, v2
	s_waitcnt lgkmcnt(0)
	v_add_f32_e32 v2, v2, v3
	v_fmamk_f32 v2, v2, 0x3c000000, v200
	v_mul_f32_e32 v3, 0x4b800000, v2
	v_cmp_gt_f32_e32 vcc, s38, v2
	s_nop 1
	v_cndmask_b32_e32 v2, v2, v3, vcc
	v_rsq_f32_e32 v2, v2
	s_nop 0
	v_mul_f32_e32 v3, 0x45800000, v2
	v_cndmask_b32_e32 v2, v2, v3, vcc
	s_waitcnt lgkmcnt(0)
	v_mbcnt_lo_u32_b32 v252, -1, 0
	v_mbcnt_hi_u32_b32 v252, -1, v252
	v_lshrrev_b32_e32 v252, 5, v252
	v_lshlrev_b32_e32 v252, 4, v252
	v_bfe_u32 v246, v202, 6, 2
	v_lshl_add_u32 v252, v246, 9, v252
	v_add_u32_e32 v252, 0x12800, v252
	global_load_dwordx2 v[242:243], v[10:11], off offset:16
	global_load_dwordx2 v[244:245], v[10:11], off offset:32
	global_load_dwordx2 v[246:247], v[10:11], off offset:48
	ds_read_b128 v[248:251], v252 offset:32
	v_mul_f32_e32 v3, v74, v2
	v_mul_f32_e32 v3, v204, v3
	v_lshlrev_b32_e32 v25, 16, v68
	v_mul_f32_e32 v3, v3, v25
	v_mul_f32_e32 v4, v76, v2
	v_mul_f32_e32 v4, v205, v4
	v_and_b32_e32 v25, 0xffff0000, v68
	v_mul_f32_e32 v4, v4, v25
	v_mul_f32_e32 v6, v77, v2
	v_mul_f32_e32 v6, v206, v6
	v_lshlrev_b32_e32 v25, 16, v69
	v_mul_f32_e32 v6, v6, v25
	v_mul_f32_e32 v41, v75, v2
	v_mul_f32_e32 v41, v207, v41
	v_and_b32_e32 v25, 0xffff0000, v69
	v_mul_f32_e32 v41, v41, v25
	v_cvt_pk_bf16_f32 v68, v3, v4
	v_cvt_pk_bf16_f32 v69, v6, v41
	global_store_dwordx2 v[10:11], v[68:69], off
	ds_read_b128 v[204:207], v252 offset:64
	s_waitcnt lgkmcnt(1)
	s_waitcnt vmcnt(3)
	v_mul_f32_e32 v3, v70, v2
	v_mul_f32_e32 v3, v248, v3
	v_lshlrev_b32_e32 v25, 16, v242
	v_mul_f32_e32 v3, v3, v25
	v_mul_f32_e32 v4, v72, v2
	v_mul_f32_e32 v4, v249, v4
	v_and_b32_e32 v25, 0xffff0000, v242
	v_mul_f32_e32 v4, v4, v25
	v_mul_f32_e32 v6, v73, v2
	v_mul_f32_e32 v6, v250, v6
	v_lshlrev_b32_e32 v25, 16, v243
	v_mul_f32_e32 v6, v6, v25
	v_mul_f32_e32 v41, v71, v2
	v_mul_f32_e32 v41, v251, v41
	v_and_b32_e32 v25, 0xffff0000, v243
	v_mul_f32_e32 v41, v41, v25
	v_cvt_pk_bf16_f32 v242, v3, v4
	v_cvt_pk_bf16_f32 v243, v6, v41
	global_store_dwordx2 v[10:11], v[242:243], off offset:16
	ds_read_b128 v[248:251], v252 offset:96
	global_load_dwordx2 v[242:243], v[10:11], off offset:64
	s_waitcnt lgkmcnt(1)
	s_waitcnt vmcnt(4)
	v_mul_f32_e32 v3, v66, v2
	v_mul_f32_e32 v3, v204, v3
	v_lshlrev_b32_e32 v25, 16, v244
	v_mul_f32_e32 v3, v3, v25
	v_mul_f32_e32 v4, v67, v2
	v_mul_f32_e32 v4, v205, v4
	v_and_b32_e32 v25, 0xffff0000, v244
	v_mul_f32_e32 v4, v4, v25
	v_mul_f32_e32 v6, v64, v2
	v_mul_f32_e32 v6, v206, v6
	v_lshlrev_b32_e32 v25, 16, v245
	v_mul_f32_e32 v6, v6, v25
	v_mul_f32_e32 v41, v65, v2
	v_mul_f32_e32 v41, v207, v41
	v_and_b32_e32 v25, 0xffff0000, v245
	v_mul_f32_e32 v41, v41, v25
	v_cvt_pk_bf16_f32 v244, v3, v4
	v_cvt_pk_bf16_f32 v245, v6, v41
	global_store_dwordx2 v[10:11], v[244:245], off offset:32
	ds_read_b128 v[204:207], v252 offset:128
	global_load_dwordx2 v[244:245], v[10:11], off offset:80
	s_waitcnt lgkmcnt(1)
	s_waitcnt vmcnt(5)
	v_mul_f32_e32 v3, v134, v2
	v_mul_f32_e32 v3, v248, v3
	v_lshlrev_b32_e32 v25, 16, v246
	v_mul_f32_e32 v3, v3, v25
	v_mul_f32_e32 v4, v147, v2
	v_mul_f32_e32 v4, v249, v4
	v_and_b32_e32 v25, 0xffff0000, v246
	v_mul_f32_e32 v4, v4, v25
	v_mul_f32_e32 v6, v149, v2
	v_mul_f32_e32 v6, v250, v6
	v_lshlrev_b32_e32 v25, 16, v247
	v_mul_f32_e32 v6, v6, v25
	v_mul_f32_e32 v41, v151, v2
	v_mul_f32_e32 v41, v251, v41
	v_and_b32_e32 v25, 0xffff0000, v247
	v_mul_f32_e32 v41, v41, v25
	v_cvt_pk_bf16_f32 v246, v3, v4
	v_cvt_pk_bf16_f32 v247, v6, v41
	global_store_dwordx2 v[10:11], v[246:247], off offset:48
	ds_read_b128 v[248:251], v252 offset:160
	global_load_dwordx2 v[246:247], v[10:11], off offset:96
	s_waitcnt lgkmcnt(1)
	s_waitcnt vmcnt(4)
	v_mul_f32_e32 v3, v58, v2
	v_mul_f32_e32 v3, v204, v3
	v_lshlrev_b32_e32 v25, 16, v242
	v_mul_f32_e32 v3, v3, v25
	v_mul_f32_e32 v4, v59, v2
	v_mul_f32_e32 v4, v205, v4
	v_and_b32_e32 v25, 0xffff0000, v242
	v_mul_f32_e32 v4, v4, v25
	v_mul_f32_e32 v6, v56, v2
	v_mul_f32_e32 v6, v206, v6
	v_lshlrev_b32_e32 v25, 16, v243
	v_mul_f32_e32 v6, v6, v25
	v_mul_f32_e32 v41, v57, v2
	v_mul_f32_e32 v41, v207, v41
	v_and_b32_e32 v25, 0xffff0000, v243
	v_mul_f32_e32 v41, v41, v25
	v_cvt_pk_bf16_f32 v242, v3, v4
	v_cvt_pk_bf16_f32 v243, v6, v41
	global_store_dwordx2 v[10:11], v[242:243], off offset:64
	ds_read_b128 v[204:207], v252 offset:192
	global_load_dwordx2 v[242:243], v[10:11], off offset:112
	s_waitcnt lgkmcnt(1)
	s_waitcnt vmcnt(4)
	v_mul_f32_e32 v3, v47, v2
	v_mul_f32_e32 v3, v248, v3
	v_lshlrev_b32_e32 v25, 16, v244
	v_mul_f32_e32 v3, v3, v25
	v_mul_f32_e32 v4, v53, v2
	v_mul_f32_e32 v4, v249, v4
	v_and_b32_e32 v25, 0xffff0000, v244
	v_mul_f32_e32 v4, v4, v25
	v_mul_f32_e32 v6, v61, v2
	v_mul_f32_e32 v6, v250, v6
	v_lshlrev_b32_e32 v25, 16, v245
	v_mul_f32_e32 v6, v6, v25
	v_mul_f32_e32 v41, v60, v2
	v_mul_f32_e32 v41, v251, v41
	v_and_b32_e32 v25, 0xffff0000, v245
	v_mul_f32_e32 v41, v41, v25
	v_cvt_pk_bf16_f32 v244, v3, v4
	v_cvt_pk_bf16_f32 v245, v6, v41
	global_store_dwordx2 v[10:11], v[244:245], off offset:80
	ds_read_b128 v[248:251], v252 offset:224
	global_load_dwordx2 v[244:245], v[10:11], off offset:128
	s_waitcnt lgkmcnt(1)
	s_waitcnt vmcnt(4)
	v_mul_f32_e32 v3, v50, v2
	v_mul_f32_e32 v3, v204, v3
	v_lshlrev_b32_e32 v25, 16, v246
	v_mul_f32_e32 v3, v3, v25
	v_mul_f32_e32 v4, v54, v2
	v_mul_f32_e32 v4, v205, v4
	v_and_b32_e32 v25, 0xffff0000, v246
	v_mul_f32_e32 v4, v4, v25
	v_mul_f32_e32 v6, v55, v2
	v_mul_f32_e32 v6, v206, v6
	v_lshlrev_b32_e32 v25, 16, v247
	v_mul_f32_e32 v6, v6, v25
	v_mul_f32_e32 v41, v51, v2
	v_mul_f32_e32 v41, v207, v41
	v_and_b32_e32 v25, 0xffff0000, v247
	v_mul_f32_e32 v41, v41, v25
	v_cvt_pk_bf16_f32 v246, v3, v4
	v_cvt_pk_bf16_f32 v247, v6, v41
	global_store_dwordx2 v[10:11], v[246:247], off offset:96
	ds_read_b128 v[204:207], v252 offset:256
	global_load_dwordx2 v[246:247], v[10:11], off offset:144
	s_waitcnt lgkmcnt(1)
	s_waitcnt vmcnt(4)
	v_mul_f32_e32 v3, v32, v2
	v_mul_f32_e32 v3, v248, v3
	v_lshlrev_b32_e32 v25, 16, v242
	v_mul_f32_e32 v3, v3, v25
	v_mul_f32_e32 v4, v33, v2
	v_mul_f32_e32 v4, v249, v4
	v_and_b32_e32 v25, 0xffff0000, v242
	v_mul_f32_e32 v4, v4, v25
	v_mul_f32_e32 v6, v42, v2
	v_mul_f32_e32 v6, v250, v6
	v_lshlrev_b32_e32 v25, 16, v243
	v_mul_f32_e32 v6, v6, v25
	v_mul_f32_e32 v41, v43, v2
	v_mul_f32_e32 v41, v251, v41
	v_and_b32_e32 v25, 0xffff0000, v243
	v_mul_f32_e32 v41, v41, v25
	v_cvt_pk_bf16_f32 v242, v3, v4
	v_cvt_pk_bf16_f32 v243, v6, v41
	global_store_dwordx2 v[10:11], v[242:243], off offset:112
	ds_read_b128 v[248:251], v252 offset:288
	global_load_dwordx2 v[242:243], v[10:11], off offset:160
	s_waitcnt lgkmcnt(1)
	s_waitcnt vmcnt(4)
	v_mul_f32_e32 v3, v46, v2
	v_mul_f32_e32 v3, v204, v3
	v_lshlrev_b32_e32 v25, 16, v244
	v_mul_f32_e32 v3, v3, v25
	v_mul_f32_e32 v4, v45, v2
	v_mul_f32_e32 v4, v205, v4
	v_and_b32_e32 v25, 0xffff0000, v244
	v_mul_f32_e32 v4, v4, v25
	v_mul_f32_e32 v6, v44, v2
	v_mul_f32_e32 v6, v206, v6
	v_lshlrev_b32_e32 v25, 16, v245
	v_mul_f32_e32 v6, v6, v25
	v_mul_f32_e32 v41, v40, v2
	v_mul_f32_e32 v41, v207, v41
	v_and_b32_e32 v25, 0xffff0000, v245
	v_mul_f32_e32 v41, v41, v25
	v_cvt_pk_bf16_f32 v244, v3, v4
	v_cvt_pk_bf16_f32 v245, v6, v41
	global_store_dwordx2 v[10:11], v[244:245], off offset:128
	ds_read_b128 v[204:207], v252 offset:320
	global_load_dwordx2 v[244:245], v[10:11], off offset:176
	s_waitcnt lgkmcnt(1)
	s_waitcnt vmcnt(4)
	v_mul_f32_e32 v3, v16, v2
	v_mul_f32_e32 v3, v248, v3
	v_lshlrev_b32_e32 v25, 16, v246
	v_mul_f32_e32 v3, v3, v25
	v_mul_f32_e32 v4, v17, v2
	v_mul_f32_e32 v4, v249, v4
	v_and_b32_e32 v25, 0xffff0000, v246
	v_mul_f32_e32 v4, v4, v25
	v_mul_f32_e32 v6, v14, v2
	v_mul_f32_e32 v6, v250, v6
	v_lshlrev_b32_e32 v25, 16, v247
	v_mul_f32_e32 v6, v6, v25
	v_mul_f32_e32 v41, v15, v2
	v_mul_f32_e32 v41, v251, v41
	v_and_b32_e32 v25, 0xffff0000, v247
	v_mul_f32_e32 v41, v41, v25
	v_cvt_pk_bf16_f32 v246, v3, v4
	v_cvt_pk_bf16_f32 v247, v6, v41
	global_store_dwordx2 v[10:11], v[246:247], off offset:144
	ds_read_b128 v[248:251], v252 offset:352
	global_load_dwordx2 v[246:247], v[10:11], off offset:192
	s_waitcnt lgkmcnt(1)
	s_waitcnt vmcnt(4)
	v_mul_f32_e32 v3, v29, v2
	v_mul_f32_e32 v3, v204, v3
	v_lshlrev_b32_e32 v25, 16, v242
	v_mul_f32_e32 v3, v3, v25
	v_mul_f32_e32 v4, v31, v2
	v_mul_f32_e32 v4, v205, v4
	v_and_b32_e32 v25, 0xffff0000, v242
	v_mul_f32_e32 v4, v4, v25
	v_mul_f32_e32 v6, v39, v2
	v_mul_f32_e32 v6, v206, v6
	v_lshlrev_b32_e32 v25, 16, v243
	v_mul_f32_e32 v6, v6, v25
	v_mul_f32_e32 v41, v38, v2
	v_mul_f32_e32 v41, v207, v41
	v_and_b32_e32 v25, 0xffff0000, v243
	v_mul_f32_e32 v41, v41, v25
	v_cvt_pk_bf16_f32 v242, v3, v4
	v_cvt_pk_bf16_f32 v243, v6, v41
	global_store_dwordx2 v[10:11], v[242:243], off offset:160
	ds_read_b128 v[204:207], v252 offset:384
	global_load_dwordx2 v[242:243], v[10:11], off offset:208
	s_waitcnt lgkmcnt(1)
	s_waitcnt vmcnt(4)
	v_mul_f32_e32 v3, v34, v2
	v_mul_f32_e32 v3, v248, v3
	v_lshlrev_b32_e32 v25, 16, v244
	v_mul_f32_e32 v3, v3, v25
	v_mul_f32_e32 v4, v36, v2
	v_mul_f32_e32 v4, v249, v4
	v_and_b32_e32 v25, 0xffff0000, v244
	v_mul_f32_e32 v4, v4, v25
	v_mul_f32_e32 v6, v37, v2
	v_mul_f32_e32 v6, v250, v6
	v_lshlrev_b32_e32 v25, 16, v245
	v_mul_f32_e32 v6, v6, v25
	v_mul_f32_e32 v41, v35, v2
	v_mul_f32_e32 v41, v251, v41
	v_and_b32_e32 v25, 0xffff0000, v245
	v_mul_f32_e32 v41, v41, v25
	v_cvt_pk_bf16_f32 v244, v3, v4
	v_cvt_pk_bf16_f32 v245, v6, v41
	global_store_dwordx2 v[10:11], v[244:245], off offset:176
	ds_read_b128 v[248:251], v252 offset:416
	global_load_dwordx2 v[244:245], v[10:11], off offset:224
	s_waitcnt lgkmcnt(1)
	s_waitcnt vmcnt(4)
	v_mul_f32_e32 v3, v26, v2
	v_mul_f32_e32 v3, v204, v3
	v_lshlrev_b32_e32 v25, 16, v246
	v_mul_f32_e32 v3, v3, v25
	v_mul_f32_e32 v4, v27, v2
	v_mul_f32_e32 v4, v205, v4
	v_and_b32_e32 v25, 0xffff0000, v246
	v_mul_f32_e32 v4, v4, v25
	v_mul_f32_e32 v6, v22, v2
	v_mul_f32_e32 v6, v206, v6
	v_lshlrev_b32_e32 v25, 16, v247
	v_mul_f32_e32 v6, v6, v25
	v_mul_f32_e32 v41, v23, v2
	v_mul_f32_e32 v41, v207, v41
	v_and_b32_e32 v25, 0xffff0000, v247
	v_mul_f32_e32 v41, v41, v25
	v_cvt_pk_bf16_f32 v246, v3, v4
	v_cvt_pk_bf16_f32 v247, v6, v41
	global_store_dwordx2 v[10:11], v[246:247], off offset:192
	ds_read_b128 v[204:207], v252 offset:448
	global_load_dwordx2 v[246:247], v[10:11], off offset:240
	s_waitcnt lgkmcnt(1)
	s_waitcnt vmcnt(4)
	v_mul_f32_e32 v3, v28, v2
	v_mul_f32_e32 v3, v248, v3
	v_lshlrev_b32_e32 v25, 16, v242
	v_mul_f32_e32 v3, v3, v25
	v_mul_f32_e32 v4, v30, v2
	v_mul_f32_e32 v4, v249, v4
	v_and_b32_e32 v25, 0xffff0000, v242
	v_mul_f32_e32 v4, v4, v25
	v_mul_f32_e32 v6, v153, v2
	v_mul_f32_e32 v6, v250, v6
	v_lshlrev_b32_e32 v25, 16, v243
	v_mul_f32_e32 v6, v6, v25
	v_mul_f32_e32 v41, v155, v2
	v_mul_f32_e32 v41, v251, v41
	v_and_b32_e32 v25, 0xffff0000, v243
	v_mul_f32_e32 v41, v41, v25
	v_cvt_pk_bf16_f32 v242, v3, v4
	v_cvt_pk_bf16_f32 v243, v6, v41
	global_store_dwordx2 v[10:11], v[242:243], off offset:208
	ds_read_b128 v[248:251], v252 offset:480
	s_waitcnt lgkmcnt(1)
	s_waitcnt vmcnt(3)
	v_mul_f32_e32 v3, v18, v2
	v_mul_f32_e32 v3, v204, v3
	v_lshlrev_b32_e32 v25, 16, v244
	v_mul_f32_e32 v3, v3, v25
	v_mul_f32_e32 v4, v19, v2
	v_mul_f32_e32 v4, v205, v4
	v_and_b32_e32 v25, 0xffff0000, v244
	v_mul_f32_e32 v4, v4, v25
	v_mul_f32_e32 v6, v8, v2
	v_mul_f32_e32 v6, v206, v6
	v_lshlrev_b32_e32 v25, 16, v245
	v_mul_f32_e32 v6, v6, v25
	v_mul_f32_e32 v41, v9, v2
	v_mul_f32_e32 v41, v207, v41
	v_and_b32_e32 v25, 0xffff0000, v245
	v_mul_f32_e32 v41, v41, v25
	v_cvt_pk_bf16_f32 v244, v3, v4
	v_cvt_pk_bf16_f32 v245, v6, v41
	global_store_dwordx2 v[10:11], v[244:245], off offset:224
	s_waitcnt lgkmcnt(0)
	s_waitcnt vmcnt(2)
	v_mul_f32_e32 v3, v5, v2
	v_mul_f32_e32 v3, v248, v3
	v_lshlrev_b32_e32 v25, 16, v246
	v_mul_f32_e32 v3, v3, v25
	v_mul_f32_e32 v4, v7, v2
	v_mul_f32_e32 v4, v249, v4
	v_and_b32_e32 v25, 0xffff0000, v246
	v_mul_f32_e32 v4, v4, v25
	v_mul_f32_e32 v6, v21, v2
	v_mul_f32_e32 v6, v250, v6
	v_lshlrev_b32_e32 v25, 16, v247
	v_mul_f32_e32 v6, v6, v25
	v_mul_f32_e32 v41, v20, v2
	v_mul_f32_e32 v41, v251, v41
	v_and_b32_e32 v25, 0xffff0000, v247
	v_mul_f32_e32 v41, v41, v25
	v_cvt_pk_bf16_f32 v246, v3, v4
	v_cvt_pk_bf16_f32 v247, v6, v41
	global_store_dwordx2 v[10:11], v[246:247], off offset:240
	s_branch .LBB0_1133
